# GEMM2 mid-K and GEMM3 epilogue row-statistic loads issued in the tile header (no in-loop vmcnt(0) drain in GEMM2)
# speedup vs baseline: 1.0024x; 1.0024x over previous
;     __host__ __device__ bool next(int i, Unit& u) const { const int L = i * G + c; if (L >= 4 * nM) return false; u.pm = L >> 2; u.pn = 0; u.kq = L & 3; return true; }
; template <class Epi, class Sched, bool ALIGN_EPI = false, bool SP2 = false>
; __device__ __forceinline__ void gemm_phase(PG8_LAS unsigned char* lds, const Gemm g, const Sched& S, const Epi& E) {
;     ...
;         const bool has_next = S.next(ui + 1, nxt);
;         const char* nA = has_next ? (const char*)g.A + (size_t)nxt.pm * tstepA + nxt.kq * g.kq_bytes : cA; const char* nB = has_next ? (const char*)g.Bt + (size_t)nxt.pn * tstepB + nxt.kq * g.kq_bytes : cB;
;     ...
; #pragma unroll
;         for (int a = 0; a < 2; ++a)
; #pragma unroll
;             for (int b = 0; b < 2; ++b)
; #pragma unroll
;                 for (int m = 0; m < 4; ++m)
; #pragma unroll
;                     for (int n = 0; n < 2; ++n) acc[a][b][m][n] = (f32x4){0.f, 0.f, 0.f, 0.f};
;         cur = nxt; cA = nA; cB = nB; ++ui;
.LBB0_433:
	s_ashr_i32 s21, s20, 31
	s_lshl_b64 s[24:25], s[20:21], 22
	v_readlane_b32 s62, v253, 35
	v_readlane_b32 s63, v253, 36
	s_add_u32 s24, s62, s24
	s_addc_u32 s25, s63, s25
	s_and_b64 s[4:5], s[4:5], exec
	v_lshl_add_u32 v184, s34, 8, v1
	v_mov_b32_e32 v4, v2
	v_mov_b32_e32 v5, v2
	s_cselect_b32 s21, s25, s31
	s_cselect_b32 s62, s24, s30
	v_ashrrev_i32_e32 v185, 31, v184
	s_add_u32 s63, s30, 0x100
	v_mov_b32_e32 v3, v2
	v_mov_b64_e32 v[8:9], v[4:5]
	v_mov_b64_e32 v[12:13], v[4:5]
	v_mov_b64_e32 v[24:25], v[4:5]
	v_mov_b64_e32 v[28:29], v[4:5]
	v_mov_b64_e32 v[40:41], v[4:5]
	v_mov_b64_e32 v[44:45], v[4:5]
	v_mov_b64_e32 v[56:57], v[4:5]
	v_mov_b64_e32 v[60:61], v[4:5]
	v_mov_b64_e32 v[16:17], v[4:5]
	v_mov_b64_e32 v[20:21], v[4:5]
	v_mov_b64_e32 v[32:33], v[4:5]
	v_mov_b64_e32 v[36:37], v[4:5]
	v_mov_b64_e32 v[48:49], v[4:5]
	v_mov_b64_e32 v[52:53], v[4:5]
	v_mov_b64_e32 v[64:65], v[4:5]
	v_mov_b64_e32 v[68:69], v[4:5]
	v_mov_b64_e32 v[72:73], v[4:5]
	v_mov_b64_e32 v[76:77], v[4:5]
	v_mov_b64_e32 v[88:89], v[4:5]
	v_mov_b64_e32 v[92:93], v[4:5]
	v_mov_b64_e32 v[104:105], v[4:5]
	v_mov_b64_e32 v[108:109], v[4:5]
	v_mov_b64_e32 v[120:121], v[4:5]
	v_mov_b64_e32 v[124:125], v[4:5]
	v_mov_b64_e32 v[80:81], v[4:5]
	v_mov_b64_e32 v[84:85], v[4:5]
	v_mov_b64_e32 v[96:97], v[4:5]
	v_mov_b64_e32 v[100:101], v[4:5]
	v_mov_b64_e32 v[112:113], v[4:5]
	v_mov_b64_e32 v[116:117], v[4:5]
	v_mov_b64_e32 v[128:129], v[4:5]
	v_mov_b64_e32 v[132:133], v[4:5]
	v_lshl_add_u64 v[134:135], v[184:185], 2, s[94:95]
	global_load_dword v236, v[134:135], off
	global_load_dword v237, v[134:135], off offset:64
	global_load_dword v238, v[134:135], off offset:128
	global_load_dword v239, v[134:135], off offset:192
	global_load_dword v240, v[134:135], off offset:512
	global_load_dword v241, v[134:135], off offset:576
	global_load_dword v242, v[134:135], off offset:640
	global_load_dword v243, v[134:135], off offset:704
	v_lshl_add_u64 v[136:137], s[28:29], 0, v[176:177]
	v_lshl_add_u64 v[138:139], s[28:29], 0, v[178:179]
	s_addc_u32 s64, s31, 0
	s_mov_b32 s65, 0
	s_mov_b64 s[4:5], 0
	v_mov_b64_e32 v[6:7], v[2:3]
	v_mov_b64_e32 v[10:11], v[2:3]
	v_mov_b64_e32 v[22:23], v[2:3]
	v_mov_b64_e32 v[26:27], v[2:3]
	v_mov_b64_e32 v[38:39], v[2:3]
	v_mov_b64_e32 v[42:43], v[2:3]
	v_mov_b64_e32 v[54:55], v[2:3]
	v_mov_b64_e32 v[58:59], v[2:3]
	v_mov_b64_e32 v[14:15], v[2:3]
	v_mov_b64_e32 v[18:19], v[2:3]
	v_mov_b64_e32 v[30:31], v[2:3]
	v_mov_b64_e32 v[34:35], v[2:3]
	v_mov_b64_e32 v[46:47], v[2:3]
	v_mov_b64_e32 v[50:51], v[2:3]
	v_mov_b64_e32 v[62:63], v[2:3]
	v_mov_b64_e32 v[66:67], v[2:3]
	v_mov_b64_e32 v[70:71], v[2:3]
	v_mov_b64_e32 v[74:75], v[2:3]
	v_mov_b64_e32 v[86:87], v[2:3]
	v_mov_b64_e32 v[90:91], v[2:3]
	v_mov_b64_e32 v[102:103], v[2:3]
	v_mov_b64_e32 v[106:107], v[2:3]
	v_mov_b64_e32 v[118:119], v[2:3]
	v_mov_b64_e32 v[122:123], v[2:3]
	v_mov_b64_e32 v[78:79], v[2:3]
	v_mov_b64_e32 v[82:83], v[2:3]
	v_mov_b64_e32 v[94:95], v[2:3]
	v_mov_b64_e32 v[98:99], v[2:3]
	v_mov_b64_e32 v[110:111], v[2:3]
	v_mov_b64_e32 v[114:115], v[2:3]
	v_mov_b64_e32 v[126:127], v[2:3]
	v_mov_b64_e32 v[130:131], v[2:3]
	s_cmpk_lg_i32 s4, 0x2000
	s_cbranch_scc1 .LBB0_436
	s_branch .LBB0_435

;     DI void midk(f32x4 (&acc)[2][2][4][2], const Unit& u, int wr, int fr) const {
;         if (!ssq_mid) return;
;         const int row0 = u.pm * BM + wr * 64 + fr;
; #pragma unroll
;         for (int ai = 0; ai < 2; ++ai)
; #pragma unroll
;             for (int m = 0; m < 4; ++m) { const float s = __builtin_amdgcn_rsqf(ssq_mid[row0 + ai * HALF + m * 16] * (1.0f / 4096.0f) + 1e-6f);
; #pragma unroll
;                 for (int bj = 0; bj < 2; ++bj)
; #pragma unroll
;                     for (int n = 0; n < 2; ++n) acc[ai][bj][m][n] *= s; }
;     }
.LBB0_435:
	v_fmamk_f32 v3, v236, 0x39800000, v193
	v_fmamk_f32 v145, v237, 0x39800000, v193
	v_fmamk_f32 v5, v238, 0x39800000, v193
	v_fmamk_f32 v146, v239, 0x39800000, v193
	v_fmamk_f32 v141, v240, 0x39800000, v193
	v_fmamk_f32 v147, v241, 0x39800000, v193
	v_fmamk_f32 v143, v242, 0x39800000, v193
	v_fmamk_f32 v149, v243, 0x39800000, v193
	v_rsq_f32_e32 v4, v3
	v_rsq_f32_e32 v140, v145
	v_rsq_f32_e32 v142, v5
	v_rsq_f32_e32 v144, v146
	v_rsq_f32_e32 v146, v141
	v_rsq_f32_e32 v148, v147
	v_rsq_f32_e32 v150, v143
	v_rsq_f32_e32 v152, v149
	v_pk_mul_f32 v[132:133], v[132:133], v[4:5] op_sel_hi:[1,0]
	v_pk_mul_f32 v[130:131], v[130:131], v[4:5] op_sel_hi:[1,0]
	v_pk_mul_f32 v[128:129], v[128:129], v[4:5] op_sel_hi:[1,0]
	v_pk_mul_f32 v[126:127], v[126:127], v[4:5] op_sel_hi:[1,0]
	v_pk_mul_f32 v[124:125], v[124:125], v[4:5] op_sel_hi:[1,0]
	v_pk_mul_f32 v[122:123], v[122:123], v[4:5] op_sel_hi:[1,0]
	v_pk_mul_f32 v[120:121], v[120:121], v[4:5] op_sel_hi:[1,0]
	v_pk_mul_f32 v[118:119], v[118:119], v[4:5] op_sel_hi:[1,0]
	v_pk_mul_f32 v[116:117], v[116:117], v[140:141] op_sel_hi:[1,0]
	v_pk_mul_f32 v[114:115], v[114:115], v[140:141] op_sel_hi:[1,0]
	v_pk_mul_f32 v[112:113], v[112:113], v[140:141] op_sel_hi:[1,0]
	v_pk_mul_f32 v[110:111], v[110:111], v[140:141] op_sel_hi:[1,0]
	v_pk_mul_f32 v[108:109], v[108:109], v[140:141] op_sel_hi:[1,0]
	v_pk_mul_f32 v[106:107], v[106:107], v[140:141] op_sel_hi:[1,0]
	v_pk_mul_f32 v[104:105], v[104:105], v[140:141] op_sel_hi:[1,0]
	v_pk_mul_f32 v[102:103], v[102:103], v[140:141] op_sel_hi:[1,0]
	v_pk_mul_f32 v[100:101], v[100:101], v[142:143] op_sel_hi:[1,0]
	v_pk_mul_f32 v[98:99], v[98:99], v[142:143] op_sel_hi:[1,0]
	v_pk_mul_f32 v[96:97], v[96:97], v[142:143] op_sel_hi:[1,0]
	v_pk_mul_f32 v[94:95], v[94:95], v[142:143] op_sel_hi:[1,0]
	v_pk_mul_f32 v[92:93], v[92:93], v[142:143] op_sel_hi:[1,0]
	v_pk_mul_f32 v[90:91], v[90:91], v[142:143] op_sel_hi:[1,0]
	v_pk_mul_f32 v[88:89], v[88:89], v[142:143] op_sel_hi:[1,0]
	v_pk_mul_f32 v[86:87], v[86:87], v[142:143] op_sel_hi:[1,0]
	v_pk_mul_f32 v[84:85], v[84:85], v[144:145] op_sel_hi:[1,0]
	v_pk_mul_f32 v[82:83], v[82:83], v[144:145] op_sel_hi:[1,0]
	v_pk_mul_f32 v[80:81], v[80:81], v[144:145] op_sel_hi:[1,0]
	v_pk_mul_f32 v[78:79], v[78:79], v[144:145] op_sel_hi:[1,0]
	v_pk_mul_f32 v[76:77], v[76:77], v[144:145] op_sel_hi:[1,0]
	v_pk_mul_f32 v[74:75], v[74:75], v[144:145] op_sel_hi:[1,0]
	v_pk_mul_f32 v[72:73], v[72:73], v[144:145] op_sel_hi:[1,0]
	v_pk_mul_f32 v[70:71], v[70:71], v[144:145] op_sel_hi:[1,0]
	v_pk_mul_f32 v[68:69], v[68:69], v[146:147] op_sel_hi:[1,0]
	v_pk_mul_f32 v[66:67], v[66:67], v[146:147] op_sel_hi:[1,0]
	v_pk_mul_f32 v[64:65], v[64:65], v[146:147] op_sel_hi:[1,0]
	v_pk_mul_f32 v[62:63], v[62:63], v[146:147] op_sel_hi:[1,0]
	v_pk_mul_f32 v[60:61], v[60:61], v[146:147] op_sel_hi:[1,0]
	v_pk_mul_f32 v[58:59], v[58:59], v[146:147] op_sel_hi:[1,0]
	v_pk_mul_f32 v[56:57], v[56:57], v[146:147] op_sel_hi:[1,0]
	v_pk_mul_f32 v[54:55], v[54:55], v[146:147] op_sel_hi:[1,0]
	v_pk_mul_f32 v[52:53], v[52:53], v[148:149] op_sel_hi:[1,0]
	v_pk_mul_f32 v[50:51], v[50:51], v[148:149] op_sel_hi:[1,0]
	v_pk_mul_f32 v[48:49], v[48:49], v[148:149] op_sel_hi:[1,0]
	v_pk_mul_f32 v[46:47], v[46:47], v[148:149] op_sel_hi:[1,0]
	v_pk_mul_f32 v[44:45], v[44:45], v[148:149] op_sel_hi:[1,0]
	v_pk_mul_f32 v[42:43], v[42:43], v[148:149] op_sel_hi:[1,0]
	v_pk_mul_f32 v[40:41], v[40:41], v[148:149] op_sel_hi:[1,0]
	v_pk_mul_f32 v[38:39], v[38:39], v[148:149] op_sel_hi:[1,0]
	v_pk_mul_f32 v[36:37], v[36:37], v[150:151] op_sel_hi:[1,0]
	v_pk_mul_f32 v[34:35], v[34:35], v[150:151] op_sel_hi:[1,0]
	v_pk_mul_f32 v[32:33], v[32:33], v[150:151] op_sel_hi:[1,0]
	v_pk_mul_f32 v[30:31], v[30:31], v[150:151] op_sel_hi:[1,0]
	v_pk_mul_f32 v[28:29], v[28:29], v[150:151] op_sel_hi:[1,0]
	v_pk_mul_f32 v[26:27], v[26:27], v[150:151] op_sel_hi:[1,0]
	v_pk_mul_f32 v[24:25], v[24:25], v[150:151] op_sel_hi:[1,0]
	v_pk_mul_f32 v[22:23], v[22:23], v[150:151] op_sel_hi:[1,0]
	v_pk_mul_f32 v[20:21], v[20:21], v[152:153] op_sel_hi:[1,0]
	v_pk_mul_f32 v[18:19], v[18:19], v[152:153] op_sel_hi:[1,0]
	v_pk_mul_f32 v[16:17], v[16:17], v[152:153] op_sel_hi:[1,0]
	v_pk_mul_f32 v[14:15], v[14:15], v[152:153] op_sel_hi:[1,0]
	v_pk_mul_f32 v[12:13], v[12:13], v[152:153] op_sel_hi:[1,0]
	v_pk_mul_f32 v[10:11], v[10:11], v[152:153] op_sel_hi:[1,0]
	v_pk_mul_f32 v[8:9], v[8:9], v[152:153] op_sel_hi:[1,0]
	v_pk_mul_f32 v[6:7], v[6:7], v[152:153] op_sel_hi:[1,0]

;     __host__ __device__ bool next(int i, Unit& u) const { const int L = i * G + c; if (L >= 4 * nM) return false; u.pm = L >> 2; u.pn = 0; u.kq = L & 3; return true; }
; #define PG8_STAGE(bufoff, gbase, voff) do { _Pragma("unroll") for (int _i = 0; _i < 2; ++_i) \
;         __builtin_amdgcn_global_load_lds((const unsigned*)((const char*)(gbase) + (voff)[_i]), (PG8_LAS unsigned*)(lds + (bufoff) + ldsw + _i * 8192), 16, 0, 0); } while (0)
;     DI void operator()(const f32x4 (&acc)[2][2][4][2], const Unit& u, int wr, int wc, int fr, int fq) const {
;     ...
;         float rs[2][4];
; #pragma unroll
;         for (int ai = 0; ai < 2; ++ai)
; #pragma unroll
;             for (int m = 0; m < 4; ++m) rs[ai][m] = ssq ? __builtin_amdgcn_rsqf(ssq[row0 + ai * HALF + m * 16] * (1.0f / 4096.0f) + 1e-6f) : 1.0f;
; template <class Epi, class Sched, bool ALIGN_EPI = false, bool SP2 = false>
; __device__ __forceinline__ void gemm_phase(PG8_LAS unsigned char* lds, const Gemm g, const Sched& S, const Epi& E) {
;     ...
;         const bool has_next = S.next(ui + 1, nxt);
;         const char* nA = has_next ? (const char*)g.A + (size_t)nxt.pm * tstepA + nxt.kq * g.kq_bytes : cA; const char* nB = has_next ? (const char*)g.Bt + (size_t)nxt.pn * tstepB + nxt.kq * g.kq_bytes : cB;
;         for (int t = 0; t < nt; t += 2) {
;             const bool last = (t == nt - 2);
;             const char* a1 = cA + (size_t)(t + 1) * kstep + (t >= g.kj_t ? g.kj_bytes : 0);
;             const char* a2 = last ? nA : cA + (size_t)(t + 2) * kstep + (t + 2 >= g.kj_t ? g.kj_bytes : 0); const char* b2 = last ? nB : cB + (size_t)(t + 2) * kstep;
;             const char* a3 = a2 + kstep; const char* b3 = b2 + kstep;
;             if (last && has_next) S.a_ready(nxt);
;             if constexpr (Epi::MIDK) { if (t == g.kj_t) E.midk(acc, cur, wr, fr); }
;             if constexpr (SP2) {
;             PG8_LDB(B0, 0, 0); PG8_LDB(B1, 0, 1); PG8_SCHED; PG8_LDA(At, 0, 0); PG8_STAGE(PG8_SA(1, 1), a1 + hstepA, voffA);
;             PG8_WAIT_V(8); PG8_WAIT_L(0); PG8_BAR; PG8_MMA(0, 0, At, B0); PG8_MMA(0, 1, At, B1); PG8_BAR; PG8_SCHED;
;             PG8_LDA(At, 0, 1); PG8_STAGE(PG8_SB(0, 0), b2, voffB); PG8_STAGE(PG8_SB(0, 1), b2 + hstepB, voffB); PG8_STAGE(PG8_SA(0, 0), a2, voffA);
;             PG8_WAIT_V(8); PG8_WAIT_L(0); PG8_BAR; PG8_MMA(1, 0, At, B0); PG8_MMA(1, 1, At, B1); PG8_BAR; PG8_SCHED;
.LBB0_524:
	s_ashr_i32 s15, s14, 31
	s_lshl_b64 s[16:17], s[14:15], 21
	s_add_u32 s16, s42, s16
	s_addc_u32 s17, s43, s17
	s_and_b64 s[18:19], s[0:1], exec
	s_cselect_b32 s15, s17, s23
	s_cselect_b32 s50, s16, s22
	s_ashr_i32 s13, s12, 31
	s_lshl_b64 s[18:19], s[12:13], 21
	v_readlane_b32 s26, v253, 37
	v_readlane_b32 s27, v253, 38
	s_add_u32 s18, s26, s18
	s_addc_u32 s19, s27, s19
	s_and_b64 s[26:27], s[0:1], exec
	s_cselect_b32 s13, s19, s25
	s_cselect_b32 s51, s18, s24
	s_add_u32 s22, s22, 0x100080
	s_addc_u32 s23, s23, 0
	s_add_u32 s52, s24, 0x100
	s_addc_u32 s53, s25, 0
	s_waitcnt lgkmcnt(0)
	s_mov_b32 s60, -2
	v_lshl_add_u32 v244, s20, 8, v157
	v_ashrrev_i32_e32 v245, 31, v244
	v_lshl_add_u64 v[244:245], v[244:245], 2, s[8:9]
	global_load_dword v236, v[244:245], off
	global_load_dword v237, v[244:245], off offset:64
	global_load_dword v238, v[244:245], off offset:128
	global_load_dword v239, v[244:245], off offset:192
	global_load_dword v240, v[244:245], off offset:512
	global_load_dword v241, v[244:245], off offset:576
	global_load_dword v242, v[244:245], off offset:640
	global_load_dword v243, v[244:245], off offset:704
	s_waitcnt vmcnt(0)
	ds_read_b128 v[146:149], v160
	ds_read_b128 v[168:171], v160 offset:1024
	ds_read_b128 v[172:175], v160 offset:2048
	ds_read_b128 v[176:179], v160 offset:3072
	ds_read_b128 v[180:183], v161
	ds_read_b128 v[184:187], v161 offset:1024
	ds_read_b128 v[188:191], v161 offset:2048
	ds_read_b128 v[192:195], v161 offset:3072
	s_add_u32 s24, s22, 0xfff00080
	s_addc_u32 s25, s23, -1
	s_cmp_eq_u32 s60, 60
	s_cselect_b32 s27, s15, s25
	s_cselect_b32 s26, s50, s24
	s_cselect_b32 s25, s13, s53
	s_cselect_b32 s24, s51, s52
	s_add_u32 s98, s24, 0x80
	s_addc_u32 s99, s25, 0
	s_add_u32 s100, s26, 0x80
	s_addc_u32 s101, s27, 0
	s_add_i32 m0, s21, 0xc000
	ds_read_b128 v[196:199], v162
	ds_read_b128 v[200:203], v162 offset:1024
	ds_read_b128 v[204:207], v162 offset:2048
	ds_read_b128 v[208:211], v162 offset:3072
	ds_read_b128 v[212:215], v162 offset:4096
	ds_read_b128 v[216:219], v162 offset:5120
	ds_read_b128 v[220:223], v162 offset:6144
	ds_read_b128 v[224:227], v162 offset:7168
	global_load_lds_dwordx4 v138, s[22:23]
	s_add_i32 m0, s21, 0xe000
	s_nop 0
	global_load_lds_dwordx4 v140, s[22:23]
	s_waitcnt vmcnt(8)
	s_waitcnt lgkmcnt(0)
	s_barrier
	s_setprio 1
	s_waitcnt lgkmcnt(0)
	v_mfma_f32_16x16x32_bf16 v[126:129], v[146:149], v[196:199], 0
	v_mfma_f32_16x16x32_bf16 v[126:129], v[168:171], v[200:203], v[126:129]
	v_mfma_f32_16x16x32_bf16 v[122:125], v[176:179], v[200:203], 0
	v_mfma_f32_16x16x32_bf16 v[122:125], v[172:175], v[196:199], v[122:125]
	v_mfma_f32_16x16x32_bf16 v[114:117], v[172:175], v[204:207], 0
	v_mfma_f32_16x16x32_bf16 v[114:117], v[176:179], v[208:211], v[114:117]
	v_mfma_f32_16x16x32_bf16 v[118:121], v[168:171], v[208:211], 0
	v_mfma_f32_16x16x32_bf16 v[118:121], v[146:149], v[204:207], v[118:121]
	v_mfma_f32_16x16x32_bf16 v[110:113], v[146:149], v[212:215], 0
	v_mfma_f32_16x16x32_bf16 v[110:113], v[168:171], v[216:219], v[110:113]
	v_mfma_f32_16x16x32_bf16 v[98:101], v[176:179], v[216:219], 0
	v_mfma_f32_16x16x32_bf16 v[98:101], v[172:175], v[212:215], v[98:101]
	v_mfma_f32_16x16x32_bf16 v[78:81], v[172:175], v[220:223], 0
	v_mfma_f32_16x16x32_bf16 v[78:81], v[176:179], v[224:227], v[78:81]
	v_mfma_f32_16x16x32_bf16 v[82:85], v[168:171], v[224:227], 0
	v_mfma_f32_16x16x32_bf16 v[82:85], v[146:149], v[220:223], v[82:85]
	v_mfma_f32_16x16x32_bf16 v[106:109], v[180:183], v[196:199], 0
	v_mfma_f32_16x16x32_bf16 v[106:109], v[184:187], v[200:203], v[106:109]
	v_mfma_f32_16x16x32_bf16 v[102:105], v[192:195], v[200:203], 0
	v_mfma_f32_16x16x32_bf16 v[102:105], v[188:191], v[196:199], v[102:105]
	v_mfma_f32_16x16x32_bf16 v[90:93], v[188:191], v[204:207], 0
	v_mfma_f32_16x16x32_bf16 v[90:93], v[192:195], v[208:211], v[90:93]
	v_mfma_f32_16x16x32_bf16 v[94:97], v[184:187], v[208:211], 0
	v_mfma_f32_16x16x32_bf16 v[94:97], v[180:183], v[204:207], v[94:97]
	v_mfma_f32_16x16x32_bf16 v[86:89], v[180:183], v[212:215], 0
	v_mfma_f32_16x16x32_bf16 v[86:89], v[184:187], v[216:219], v[86:89]
	v_mfma_f32_16x16x32_bf16 v[74:77], v[192:195], v[216:219], 0
	v_mfma_f32_16x16x32_bf16 v[74:77], v[188:191], v[212:215], v[74:77]
	v_mfma_f32_16x16x32_bf16 v[66:69], v[188:191], v[220:223], 0
	v_mfma_f32_16x16x32_bf16 v[66:69], v[192:195], v[224:227], v[66:69]
	s_setprio 2
	s_barrier
	v_mfma_f32_16x16x32_bf16 v[70:73], v[184:187], v[224:227], 0
	v_mfma_f32_16x16x32_bf16 v[70:73], v[180:183], v[220:223], v[70:73]
	s_setprio 0
	s_add_i32 s61, s38, s3
	s_mov_b32 m0, s61
	ds_read_b128 v[196:199], v162 offset:16384
	ds_read_b128 v[200:203], v162 offset:17408
	ds_read_b128 v[204:207], v162 offset:18432
	ds_read_b128 v[208:211], v162 offset:19456
	ds_read_b128 v[212:215], v162 offset:20480
	ds_read_b128 v[216:219], v162 offset:21504
	ds_read_b128 v[220:223], v162 offset:22528
	ds_read_b128 v[224:227], v162 offset:23552
	global_load_lds_dwordx4 v136, s[24:25]
	s_add_i32 m0, s61, 0x2000
	s_add_u32 s62, s24, 0x100000
	s_addc_u32 s63, s25, 0
	s_add_i32 s61, s39, s3
	global_load_lds_dwordx4 v134, s[24:25]
	s_mov_b32 m0, s61
	s_nop 0
	global_load_lds_dwordx4 v136, s[62:63]
	s_add_i32 m0, s61, 0x2000
	s_nop 0
	global_load_lds_dwordx4 v134, s[62:63]
	s_mov_b32 m0, s21
	s_nop 0
	global_load_lds_dwordx4 v130, s[26:27]
	s_mov_b32 m0, s30
	s_nop 0
	global_load_lds_dwordx4 v132, s[26:27]
	s_waitcnt vmcnt(8)
	s_waitcnt lgkmcnt(0)
	s_barrier
; #define PG8_STAGE(bufoff, gbase, voff) do { _Pragma("unroll") for (int _i = 0; _i < 2; ++_i) \
;         __builtin_amdgcn_global_load_lds((const unsigned*)((const char*)(gbase) + (voff)[_i]), (PG8_LAS unsigned*)(lds + (bufoff) + ldsw + _i * 8192), 16, 0, 0); } while (0)
; #define PG8_LDA(dst, b, h) do { _Pragma("unroll") for (int m = 0; m < 4; ++m) _Pragma("unroll") for (int k = 0; k < 2; ++k) dst[m][k] = *(const PG8_LAS bf16x8*)(lds + PG8_SA(b, h) + aoff + m * 2048 + k * 1024); } while (0)
; #define PG8_LDB(dst, b, h) do { _Pragma("unroll") for (int n = 0; n < 2; ++n) _Pragma("unroll") for (int k = 0; k < 2; ++k) dst[n][k] = *(const PG8_LAS bf16x8*)(lds + PG8_SB(b, h) + boff + n * 2048 + k * 1024); } while (0)
; #define PG8_MMA(ai, bj, At, Bt) do { __builtin_amdgcn_s_setprio(1); _Pragma("unroll") for (int m = 0; m < 4; ++m) _Pragma("unroll") for (int n = 0; n < 2; ++n) _Pragma("unroll") for (int k = 0; k < 2; ++k) \
;         acc[ai][bj][m][n] = __builtin_amdgcn_mfma_f32_16x16x32_bf16(Bt[n][k], At[m][k], acc[ai][bj][m][n], 0, 0, 0); __builtin_amdgcn_s_setprio(0); } while (0)
; #define PG8_WAIT_V(n) asm volatile("s_waitcnt vmcnt(" #n ")" ::: "memory")
; #define PG8_WAIT_L(n) asm volatile("s_waitcnt lgkmcnt(" #n ")" ::: "memory")
; #define PG8_BAR __builtin_amdgcn_s_barrier()
; #define PG8_SCHED __builtin_amdgcn_sched_barrier(0)
; template <class Epi, class Sched, bool ALIGN_EPI = false, bool SP2 = false>
; __device__ __forceinline__ void gemm_phase(PG8_LAS unsigned char* lds, const Gemm g, const Sched& S, const Epi& E) {
;     ...
;             PG8_WAIT_V(8); PG8_WAIT_L(0); PG8_BAR; PG8_MMA(0, 0, At, B0); PG8_MMA(0, 1, At, B1); PG8_BAR; PG8_SCHED;
;             PG8_LDA(At, 0, 1); PG8_STAGE(PG8_SB(0, 0), b2, voffB); PG8_STAGE(PG8_SB(0, 1), b2 + hstepB, voffB); PG8_STAGE(PG8_SA(0, 0), a2, voffA);
;             PG8_WAIT_V(8); PG8_WAIT_L(0); PG8_BAR; PG8_MMA(1, 0, At, B0); PG8_MMA(1, 1, At, B1); PG8_BAR; PG8_SCHED;
;             PG8_LDB(B0, 1, 0); PG8_LDB(B1, 1, 1); PG8_SCHED; PG8_LDA(At, 1, 0); PG8_STAGE(PG8_SA(0, 1), a2 + hstepA, voffA);
;             PG8_WAIT_V(8); PG8_WAIT_L(0); PG8_BAR; PG8_MMA(0, 0, At, B0); PG8_MMA(0, 1, At, B1); PG8_BAR; PG8_SCHED;
	s_setprio 1
	s_waitcnt lgkmcnt(0)
	v_mfma_f32_16x16x32_bf16 v[62:65], v[146:149], v[196:199], 0
	v_mfma_f32_16x16x32_bf16 v[62:65], v[168:171], v[200:203], v[62:65]
	v_mfma_f32_16x16x32_bf16 v[58:61], v[176:179], v[200:203], 0
	v_mfma_f32_16x16x32_bf16 v[58:61], v[172:175], v[196:199], v[58:61]
	v_mfma_f32_16x16x32_bf16 v[46:49], v[172:175], v[204:207], 0
	v_mfma_f32_16x16x32_bf16 v[46:49], v[176:179], v[208:211], v[46:49]
	v_mfma_f32_16x16x32_bf16 v[54:57], v[168:171], v[208:211], 0
	v_mfma_f32_16x16x32_bf16 v[54:57], v[146:149], v[204:207], v[54:57]
	v_mfma_f32_16x16x32_bf16 v[38:41], v[146:149], v[212:215], 0
	v_mfma_f32_16x16x32_bf16 v[38:41], v[168:171], v[216:219], v[38:41]
	v_mfma_f32_16x16x32_bf16 v[30:33], v[176:179], v[216:219], 0
	v_mfma_f32_16x16x32_bf16 v[30:33], v[172:175], v[212:215], v[30:33]
	v_mfma_f32_16x16x32_bf16 v[14:17], v[172:175], v[220:223], 0
	v_mfma_f32_16x16x32_bf16 v[14:17], v[176:179], v[224:227], v[14:17]
	v_mfma_f32_16x16x32_bf16 v[22:25], v[168:171], v[224:227], 0
	v_mfma_f32_16x16x32_bf16 v[22:25], v[146:149], v[220:223], v[22:25]
	v_mfma_f32_16x16x32_bf16 v[50:53], v[180:183], v[196:199], 0
	v_mfma_f32_16x16x32_bf16 v[50:53], v[184:187], v[200:203], v[50:53]
	v_mfma_f32_16x16x32_bf16 v[42:45], v[192:195], v[200:203], 0
	v_mfma_f32_16x16x32_bf16 v[42:45], v[188:191], v[196:199], v[42:45]
	v_mfma_f32_16x16x32_bf16 v[26:29], v[188:191], v[204:207], 0
	v_mfma_f32_16x16x32_bf16 v[26:29], v[192:195], v[208:211], v[26:29]
	v_mfma_f32_16x16x32_bf16 v[34:37], v[184:187], v[208:211], 0
	v_mfma_f32_16x16x32_bf16 v[34:37], v[180:183], v[204:207], v[34:37]
	v_mfma_f32_16x16x32_bf16 v[18:21], v[180:183], v[212:215], 0
	v_mfma_f32_16x16x32_bf16 v[18:21], v[184:187], v[216:219], v[18:21]
	v_mfma_f32_16x16x32_bf16 v[10:13], v[192:195], v[216:219], 0
	v_mfma_f32_16x16x32_bf16 v[10:13], v[188:191], v[212:215], v[10:13]
	v_mfma_f32_16x16x32_bf16 v[2:5], v[188:191], v[220:223], 0
	v_mfma_f32_16x16x32_bf16 v[2:5], v[192:195], v[224:227], v[2:5]
	s_setprio 2
	s_barrier
	v_mfma_f32_16x16x32_bf16 v[6:9], v[184:187], v[224:227], 0
	v_mfma_f32_16x16x32_bf16 v[6:9], v[180:183], v[220:223], v[6:9]
	s_setprio 0
	s_add_i32 s61, 0, 0x18000
	v_add_u32_e32 v150, s61, v158
	s_add_i32 s62, 0, 0x1c000
	ds_read_b128 v[146:149], v150
	ds_read_b128 v[168:171], v150 offset:1024
	ds_read_b128 v[172:175], v150 offset:2048
	ds_read_b128 v[176:179], v150 offset:3072
	v_add_u32_e32 v150, s62, v158
	ds_read_b128 v[180:183], v150
	ds_read_b128 v[184:187], v150 offset:1024
	ds_read_b128 v[188:191], v150 offset:2048
	ds_read_b128 v[192:195], v150 offset:3072
	s_add_u32 s26, s26, 0x100000
	s_addc_u32 s27, s27, 0
	s_mov_b32 m0, s31
	ds_read_b128 v[196:199], v162 offset:32768
	ds_read_b128 v[200:203], v162 offset:33792
	ds_read_b128 v[204:207], v162 offset:34816
	ds_read_b128 v[208:211], v162 offset:35840
	ds_read_b128 v[212:215], v162 offset:36864
	ds_read_b128 v[216:219], v162 offset:37888
	ds_read_b128 v[220:223], v162 offset:38912
	ds_read_b128 v[224:227], v162 offset:39936
	global_load_lds_dwordx4 v130, s[26:27]
	s_mov_b32 m0, s33
	s_nop 0
	global_load_lds_dwordx4 v132, s[26:27]
	s_waitcnt vmcnt(8)
	s_waitcnt lgkmcnt(0)
	s_barrier
	s_setprio 1
	s_waitcnt lgkmcnt(0)
	v_mfma_f32_16x16x32_bf16 v[126:129], v[146:149], v[196:199], v[126:129]
	v_mfma_f32_16x16x32_bf16 v[126:129], v[168:171], v[200:203], v[126:129]
	v_mfma_f32_16x16x32_bf16 v[122:125], v[176:179], v[200:203], v[122:125]
	v_mfma_f32_16x16x32_bf16 v[122:125], v[172:175], v[196:199], v[122:125]
	v_mfma_f32_16x16x32_bf16 v[114:117], v[172:175], v[204:207], v[114:117]
	v_mfma_f32_16x16x32_bf16 v[114:117], v[176:179], v[208:211], v[114:117]
	v_mfma_f32_16x16x32_bf16 v[118:121], v[168:171], v[208:211], v[118:121]
	v_mfma_f32_16x16x32_bf16 v[118:121], v[146:149], v[204:207], v[118:121]
	v_mfma_f32_16x16x32_bf16 v[110:113], v[146:149], v[212:215], v[110:113]
	v_mfma_f32_16x16x32_bf16 v[110:113], v[168:171], v[216:219], v[110:113]
	v_mfma_f32_16x16x32_bf16 v[98:101], v[176:179], v[216:219], v[98:101]
	v_mfma_f32_16x16x32_bf16 v[98:101], v[172:175], v[212:215], v[98:101]
	v_mfma_f32_16x16x32_bf16 v[78:81], v[172:175], v[220:223], v[78:81]
	v_mfma_f32_16x16x32_bf16 v[78:81], v[176:179], v[224:227], v[78:81]
	v_mfma_f32_16x16x32_bf16 v[82:85], v[168:171], v[224:227], v[82:85]
	v_mfma_f32_16x16x32_bf16 v[82:85], v[146:149], v[220:223], v[82:85]
	v_mfma_f32_16x16x32_bf16 v[106:109], v[180:183], v[196:199], v[106:109]
	v_mfma_f32_16x16x32_bf16 v[106:109], v[184:187], v[200:203], v[106:109]
	v_mfma_f32_16x16x32_bf16 v[102:105], v[192:195], v[200:203], v[102:105]
	v_mfma_f32_16x16x32_bf16 v[102:105], v[188:191], v[196:199], v[102:105]
	v_mfma_f32_16x16x32_bf16 v[90:93], v[188:191], v[204:207], v[90:93]
	v_mfma_f32_16x16x32_bf16 v[90:93], v[192:195], v[208:211], v[90:93]
	v_mfma_f32_16x16x32_bf16 v[94:97], v[184:187], v[208:211], v[94:97]
	v_mfma_f32_16x16x32_bf16 v[94:97], v[180:183], v[204:207], v[94:97]
	v_mfma_f32_16x16x32_bf16 v[86:89], v[180:183], v[212:215], v[86:89]
	v_mfma_f32_16x16x32_bf16 v[86:89], v[184:187], v[216:219], v[86:89]
	v_mfma_f32_16x16x32_bf16 v[74:77], v[192:195], v[216:219], v[74:77]
	v_mfma_f32_16x16x32_bf16 v[74:77], v[188:191], v[212:215], v[74:77]
	v_mfma_f32_16x16x32_bf16 v[66:69], v[188:191], v[220:223], v[66:69]
	v_mfma_f32_16x16x32_bf16 v[66:69], v[192:195], v[224:227], v[66:69]
	s_setprio 2
	s_barrier
; #define PG8_STAGE(bufoff, gbase, voff) do { _Pragma("unroll") for (int _i = 0; _i < 2; ++_i) \
;         __builtin_amdgcn_global_load_lds((const unsigned*)((const char*)(gbase) + (voff)[_i]), (PG8_LAS unsigned*)(lds + (bufoff) + ldsw + _i * 8192), 16, 0, 0); } while (0)
; #define PG8_LDA(dst, b, h) do { _Pragma("unroll") for (int m = 0; m < 4; ++m) _Pragma("unroll") for (int k = 0; k < 2; ++k) dst[m][k] = *(const PG8_LAS bf16x8*)(lds + PG8_SA(b, h) + aoff + m * 2048 + k * 1024); } while (0)
; #define PG8_BAR __builtin_amdgcn_s_barrier()
; template <class Epi, class Sched, bool ALIGN_EPI = false, bool SP2 = false>
; __device__ __forceinline__ void gemm_phase(PG8_LAS unsigned char* lds, const Gemm g, const Sched& S, const Epi& E) {
;     ...
;         for (int t = 0; t < nt; t += 2) {
;             const bool last = (t == nt - 2);
;             const char* a1 = cA + (size_t)(t + 1) * kstep + (t >= g.kj_t ? g.kj_bytes : 0);
;             const char* a2 = last ? nA : cA + (size_t)(t + 2) * kstep + (t + 2 >= g.kj_t ? g.kj_bytes : 0); const char* b2 = last ? nB : cB + (size_t)(t + 2) * kstep;
;             const char* a3 = a2 + kstep; const char* b3 = b2 + kstep;
;             if (last && has_next) S.a_ready(nxt);
;             if constexpr (Epi::MIDK) { if (t == g.kj_t) E.midk(acc, cur, wr, fr); }
;             if constexpr (SP2) {
;             PG8_LDB(B0, 0, 0); PG8_LDB(B1, 0, 1); PG8_SCHED; PG8_LDA(At, 0, 0); PG8_STAGE(PG8_SA(1, 1), a1 + hstepA, voffA);
;             PG8_WAIT_V(8); PG8_WAIT_L(0); PG8_BAR; PG8_MMA(0, 0, At, B0); PG8_MMA(0, 1, At, B1); PG8_BAR; PG8_SCHED;
;             PG8_LDA(At, 0, 1); PG8_STAGE(PG8_SB(0, 0), b2, voffB); PG8_STAGE(PG8_SB(0, 1), b2 + hstepB, voffB); PG8_STAGE(PG8_SA(0, 0), a2, voffA);
;             PG8_WAIT_V(8); PG8_WAIT_L(0); PG8_BAR; PG8_MMA(1, 0, At, B0); PG8_MMA(1, 1, At, B1); PG8_BAR; PG8_SCHED;
;             PG8_LDB(B0, 1, 0); PG8_LDB(B1, 1, 1); PG8_SCHED; PG8_LDA(At, 1, 0); PG8_STAGE(PG8_SA(0, 1), a2 + hstepA, voffA);
;             PG8_WAIT_V(8); PG8_WAIT_L(0); PG8_BAR; PG8_MMA(0, 0, At, B0); PG8_MMA(0, 1, At, B1); PG8_BAR; PG8_SCHED;
;             PG8_LDA(At, 1, 1); PG8_STAGE(PG8_SB(1, 0), b3, voffB); PG8_STAGE(PG8_SB(1, 1), b3 + hstepB, voffB); PG8_STAGE(PG8_SA(1, 0), a3, voffA);
;             PG8_WAIT_V(8); PG8_WAIT_L(0); PG8_BAR; PG8_MMA(1, 0, At, B0); PG8_MMA(1, 1, At, B1); PG8_BAR; PG8_SCHED;
	v_mfma_f32_16x16x32_bf16 v[70:73], v[184:187], v[224:227], v[70:73]
	v_mfma_f32_16x16x32_bf16 v[70:73], v[180:183], v[220:223], v[70:73]
	s_setprio 0
	s_add_i32 s26, s61, s3
	s_mov_b32 m0, s26
	ds_read_b128 v[196:199], v162 offset:49152
	ds_read_b128 v[200:203], v162 offset:50176
	ds_read_b128 v[204:207], v162 offset:51200
	ds_read_b128 v[208:211], v162 offset:52224
	ds_read_b128 v[212:215], v162 offset:53248
	ds_read_b128 v[216:219], v162 offset:54272
	ds_read_b128 v[220:223], v162 offset:55296
	ds_read_b128 v[224:227], v162 offset:56320
	global_load_lds_dwordx4 v136, s[98:99]
	s_add_i32 m0, s26, 0x2000
	s_add_u32 s24, s24, 0x100080
	s_addc_u32 s25, s25, 0
	s_add_i32 s26, s62, s3
	global_load_lds_dwordx4 v134, s[98:99]
	s_mov_b32 m0, s26
	s_nop 0
	global_load_lds_dwordx4 v136, s[24:25]
	s_add_i32 m0, s26, 0x2000
	s_nop 0
	global_load_lds_dwordx4 v134, s[24:25]
	s_mov_b32 m0, s35
	s_nop 0
	global_load_lds_dwordx4 v130, s[100:101]
	s_mov_b32 m0, s36
	s_nop 0
	global_load_lds_dwordx4 v132, s[100:101]
	s_waitcnt vmcnt(8)
	s_waitcnt lgkmcnt(0)
	s_barrier
	s_setprio 1
	s_waitcnt lgkmcnt(0)
	v_mfma_f32_16x16x32_bf16 v[62:65], v[146:149], v[196:199], v[62:65]
	v_mfma_f32_16x16x32_bf16 v[62:65], v[168:171], v[200:203], v[62:65]
	v_mfma_f32_16x16x32_bf16 v[58:61], v[176:179], v[200:203], v[58:61]
	v_mfma_f32_16x16x32_bf16 v[58:61], v[172:175], v[196:199], v[58:61]
	v_mfma_f32_16x16x32_bf16 v[46:49], v[172:175], v[204:207], v[46:49]
	v_mfma_f32_16x16x32_bf16 v[46:49], v[176:179], v[208:211], v[46:49]
	v_mfma_f32_16x16x32_bf16 v[54:57], v[168:171], v[208:211], v[54:57]
	v_mfma_f32_16x16x32_bf16 v[54:57], v[146:149], v[204:207], v[54:57]
	v_mfma_f32_16x16x32_bf16 v[38:41], v[146:149], v[212:215], v[38:41]
	v_mfma_f32_16x16x32_bf16 v[38:41], v[168:171], v[216:219], v[38:41]
	v_mfma_f32_16x16x32_bf16 v[30:33], v[176:179], v[216:219], v[30:33]
	v_mfma_f32_16x16x32_bf16 v[30:33], v[172:175], v[212:215], v[30:33]
	v_mfma_f32_16x16x32_bf16 v[14:17], v[172:175], v[220:223], v[14:17]
	v_mfma_f32_16x16x32_bf16 v[14:17], v[176:179], v[224:227], v[14:17]
	v_mfma_f32_16x16x32_bf16 v[22:25], v[168:171], v[224:227], v[22:25]
	v_mfma_f32_16x16x32_bf16 v[22:25], v[146:149], v[220:223], v[22:25]
	v_mfma_f32_16x16x32_bf16 v[50:53], v[180:183], v[196:199], v[50:53]
	v_mfma_f32_16x16x32_bf16 v[50:53], v[184:187], v[200:203], v[50:53]
	v_mfma_f32_16x16x32_bf16 v[42:45], v[192:195], v[200:203], v[42:45]
	v_mfma_f32_16x16x32_bf16 v[42:45], v[188:191], v[196:199], v[42:45]
	v_mfma_f32_16x16x32_bf16 v[26:29], v[188:191], v[204:207], v[26:29]
	v_mfma_f32_16x16x32_bf16 v[26:29], v[192:195], v[208:211], v[26:29]
	v_mfma_f32_16x16x32_bf16 v[34:37], v[184:187], v[208:211], v[34:37]
	v_mfma_f32_16x16x32_bf16 v[34:37], v[180:183], v[204:207], v[34:37]
	v_mfma_f32_16x16x32_bf16 v[18:21], v[180:183], v[212:215], v[18:21]
	v_mfma_f32_16x16x32_bf16 v[18:21], v[184:187], v[216:219], v[18:21]
	v_mfma_f32_16x16x32_bf16 v[10:13], v[192:195], v[216:219], v[10:13]
	v_mfma_f32_16x16x32_bf16 v[10:13], v[188:191], v[212:215], v[10:13]
	v_mfma_f32_16x16x32_bf16 v[2:5], v[188:191], v[220:223], v[2:5]
	v_mfma_f32_16x16x32_bf16 v[2:5], v[192:195], v[224:227], v[2:5]
	s_setprio 2
	s_barrier
	v_mfma_f32_16x16x32_bf16 v[6:9], v[184:187], v[224:227], v[6:9]
	v_mfma_f32_16x16x32_bf16 v[6:9], v[180:183], v[220:223], v[6:9]
	s_setprio 0
	s_add_i32 s60, s60, 2
	s_add_u32 s22, s22, 0x100
	s_addc_u32 s23, s23, 0
	s_add_u32 s52, s52, 0x100
	s_addc_u32 s53, s53, 0

; DI unsigned cvt_pk_bf16(float lo, float hi) { f32x2 v = {lo, hi}; bf16v2 b = __builtin_convertvector(v, bf16v2); return __builtin_bit_cast(unsigned, b); }
;     DI void operator()(const f32x4 (&acc)[2][2][4][2], const Unit& u, int wr, int wc, int fr, int fq) const {
;         const int row0 = u.pm * BM + wr * 64 + fr; const int col0 = u.pn * BM + wc * 32 + 8 * fq;
;         float rs[2][4];
; #pragma unroll
;         for (int ai = 0; ai < 2; ++ai)
; #pragma unroll
;             for (int m = 0; m < 4; ++m) rs[ai][m] = ssq ? __builtin_amdgcn_rsqf(ssq[row0 + ai * HALF + m * 16] * (1.0f / 4096.0f) + 1e-6f) : 1.0f;
; #pragma unroll
;         for (int ai = 0; ai < 2; ++ai)
; #pragma unroll
;             for (int m = 0; m < 4; ++m) { bf16_t* rowp = O + (size_t)(row0 + ai * HALF + m * 16) * ldc + col0; const float s = rs[ai][m];
; #pragma unroll
;                 for (int bj = 0; bj < 2; ++bj) { const f32x4 v0 = acc[ai][bj][m][0] * s, v1 = acc[ai][bj][m][1] * s;
;                     u32x4 w; w.x = cvt_pk_bf16(v0[0], v0[1]); w.y = cvt_pk_bf16(v0[2], v0[3]); w.z = cvt_pk_bf16(v1[0], v1[1]); w.w = cvt_pk_bf16(v1[2], v1[3]);
;                     *(u32x4*)(rowp + bj * HALF) = w; } }
.LBB0_528:
	v_lshl_add_u32 v148, s20, 8, v157
	v_ashrrev_i32_e32 v149, 31, v148
	v_lshl_add_u64 v[146:147], v[148:149], 2, s[8:9]
	v_mov_b32_e32 v149, v236
	v_mov_b32_e32 v150, v237
	v_mov_b32_e32 v167, v238
	v_mov_b32_e32 v174, v239
	v_mov_b32_e32 v175, v240
	v_mov_b32_e32 v176, v241
	v_mov_b32_e32 v177, v242
	v_mov_b32_e32 v178, v243
	v_readlane_b32 s22, v253, 28
	v_lshl_or_b32 v164, s41, 8, v159
	v_readlane_b32 s23, v253, 29
	v_ashrrev_i32_e32 v165, 31, v164
	v_add_u32_e32 v179, 0x80, v148
	v_mov_b64_e32 v[146:147], s[22:23]
	v_mad_i64_i32 v[168:169], s[22:23], v148, s40, v[146:147]
	v_or_b32_e32 v170, 16, v148
	v_or_b32_e32 v172, 32, v148
	v_lshlrev_b64 v[164:165], 1, v[164:165]
	v_mad_i64_i32 v[170:171], s[22:23], v170, s40, v[146:147]
	v_mad_i64_i32 v[172:173], s[22:23], v172, s40, v[146:147]
	v_lshl_add_u64 v[168:169], v[168:169], 0, v[164:165]
	v_lshl_add_u64 v[170:171], v[170:171], 0, v[164:165]
	v_lshl_add_u64 v[172:173], v[172:173], 0, v[164:165]
	v_add_u32_e32 v181, 0xb0, v148
	s_andn2_b64 vcc, exec, s[0:1]
	s_mov_b64 s[0:1], -1
	s_waitcnt vmcnt(0)
	v_fmamk_f32 v149, v149, 0x39800000, v163
	v_fmamk_f32 v150, v150, 0x39800000, v163
	v_fmamk_f32 v167, v167, 0x39800000, v163
	v_fmamk_f32 v180, v174, 0x39800000, v163
	v_rsq_f32_e32 v174, v149
	v_fmamk_f32 v183, v176, 0x39800000, v163
	v_rsq_f32_e32 v176, v150
	v_fmamk_f32 v185, v178, 0x39800000, v163
	v_rsq_f32_e32 v178, v167
	v_fmamk_f32 v175, v175, 0x39800000, v163
	v_fmamk_f32 v177, v177, 0x39800000, v163
	v_pk_mul_f32 v[128:129], v[128:129], v[174:175] op_sel_hi:[1,0]
	v_pk_mul_f32 v[126:127], v[126:127], v[174:175] op_sel_hi:[1,0]
	v_pk_mul_f32 v[124:125], v[124:125], v[174:175] op_sel_hi:[1,0]
	v_pk_mul_f32 v[122:123], v[122:123], v[174:175] op_sel_hi:[1,0]
	v_rsq_f32_e32 v182, v175
	v_rsq_f32_e32 v186, v177
	v_pk_mul_f32 v[108:109], v[108:109], v[174:175] op_sel_hi:[1,0]
	v_pk_mul_f32 v[106:107], v[106:107], v[174:175] op_sel_hi:[1,0]
	v_pk_mul_f32 v[104:105], v[104:105], v[174:175] op_sel_hi:[1,0]
	v_pk_mul_f32 v[102:103], v[102:103], v[174:175] op_sel_hi:[1,0]
	v_pk_mul_f32 v[120:121], v[120:121], v[176:177] op_sel_hi:[1,0]
	v_pk_mul_f32 v[118:119], v[118:119], v[176:177] op_sel_hi:[1,0]
	v_pk_mul_f32 v[116:117], v[116:117], v[176:177] op_sel_hi:[1,0]
	v_pk_mul_f32 v[114:115], v[114:115], v[176:177] op_sel_hi:[1,0]
	v_pk_mul_f32 v[174:175], v[96:97], v[176:177] op_sel_hi:[1,0]
	v_pk_mul_f32 v[188:189], v[94:95], v[176:177] op_sel_hi:[1,0]
	v_pk_mul_f32 v[190:191], v[92:93], v[176:177] op_sel_hi:[1,0]
	v_pk_mul_f32 v[176:177], v[90:91], v[176:177] op_sel_hi:[1,0]
	v_pk_mul_f32 v[112:113], v[112:113], v[178:179] op_sel_hi:[1,0]
	v_pk_mul_f32 v[110:111], v[110:111], v[178:179] op_sel_hi:[1,0]
	v_pk_mul_f32 v[192:193], v[100:101], v[178:179] op_sel_hi:[1,0]
	v_pk_mul_f32 v[194:195], v[98:99], v[178:179] op_sel_hi:[1,0]
	v_pk_mul_f32 v[196:197], v[88:89], v[178:179] op_sel_hi:[1,0]
	v_pk_mul_f32 v[198:199], v[86:87], v[178:179] op_sel_hi:[1,0]
	v_cvt_pk_bf16_f32 v86, v126, v127
	v_cvt_pk_bf16_f32 v87, v128, v129
	v_cvt_pk_bf16_f32 v88, v122, v123
	v_cvt_pk_bf16_f32 v89, v124, v125
	v_rsq_f32_e32 v180, v180
	v_cvt_pk_bf16_f32 v90, v106, v107
	v_cvt_pk_bf16_f32 v91, v108, v109
	v_cvt_pk_bf16_f32 v92, v102, v103
	v_cvt_pk_bf16_f32 v93, v104, v105
	v_cvt_pk_bf16_f32 v94, v118, v119
	v_cvt_pk_bf16_f32 v95, v120, v121
	v_cvt_pk_bf16_f32 v96, v114, v115
	v_cvt_pk_bf16_f32 v97, v116, v117
	v_cvt_pk_bf16_f32 v98, v188, v189
	v_cvt_pk_bf16_f32 v99, v174, v175
	v_cvt_pk_bf16_f32 v100, v176, v177
	v_cvt_pk_bf16_f32 v101, v190, v191
	v_cvt_pk_bf16_f32 v102, v110, v111
	v_cvt_pk_bf16_f32 v103, v112, v113
	v_cvt_pk_bf16_f32 v104, v194, v195
	v_cvt_pk_bf16_f32 v105, v192, v193
	global_store_dwordx4 v[168:169], v[86:89], off
	global_store_dwordx4 v[168:169], v[90:93], off offset:256
	global_store_dwordx4 v[170:171], v[94:97], off
	global_store_dwordx4 v[170:171], v[98:101], off offset:256
	global_store_dwordx4 v[172:173], v[102:105], off
	v_pk_mul_f32 v[86:87], v[76:77], v[178:179] op_sel_hi:[1,0]
	v_pk_mul_f32 v[76:77], v[74:75], v[178:179] op_sel_hi:[1,0]
	v_cvt_pk_bf16_f32 v74, v198, v199
	v_cvt_pk_bf16_f32 v75, v196, v197
	v_cvt_pk_bf16_f32 v76, v76, v77
	v_cvt_pk_bf16_f32 v77, v86, v87
	global_store_dwordx4 v[172:173], v[74:77], off offset:256
	v_pk_mul_f32 v[80:81], v[80:81], v[180:181] op_sel_hi:[1,0]
	v_pk_mul_f32 v[78:79], v[78:79], v[180:181] op_sel_hi:[1,0]
	v_or_b32_e32 v74, 48, v148
	v_mad_i64_i32 v[74:75], s[22:23], v74, s40, v[146:147]
	v_lshl_add_u64 v[86:87], v[74:75], 0, v[164:165]
	v_pk_mul_f32 v[76:77], v[84:85], v[180:181] op_sel_hi:[1,0]
	v_pk_mul_f32 v[74:75], v[82:83], v[180:181] op_sel_hi:[1,0]
; DI unsigned cvt_pk_bf16(float lo, float hi) { f32x2 v = {lo, hi}; bf16v2 b = __builtin_convertvector(v, bf16v2); return __builtin_bit_cast(unsigned, b); }
; #define PG8_BAR __builtin_amdgcn_s_barrier()
;     DI void operator()(const f32x4 (&acc)[2][2][4][2], const Unit& u, int wr, int wc, int fr, int fq) const {
;     ...
;             for (int m = 0; m < 4; ++m) { bf16_t* rowp = O + (size_t)(row0 + ai * HALF + m * 16) * ldc + col0; const float s = rs[ai][m];
; #pragma unroll
;                 for (int bj = 0; bj < 2; ++bj) { const f32x4 v0 = acc[ai][bj][m][0] * s, v1 = acc[ai][bj][m][1] * s;
;                     u32x4 w; w.x = cvt_pk_bf16(v0[0], v0[1]); w.y = cvt_pk_bf16(v0[2], v0[3]); w.z = cvt_pk_bf16(v1[0], v1[1]); w.w = cvt_pk_bf16(v1[2], v1[3]);
;                     *(u32x4*)(rowp + bj * HALF) = w; } }
; template <class Epi, class Sched, bool ALIGN_EPI = false, bool SP2 = false>
; __device__ __forceinline__ void gemm_phase(PG8_LAS unsigned char* lds, const Gemm g, const Sched& S, const Epi& E) {
;     ...
;         if constexpr (ALIGN_EPI) { if (wr == 0) PG8_BAR; }
;         if constexpr (!Epi::AFTER_DRAIN) { E(acc, cur, wr, wc, fr, fq); S.done(cur); }
;         if (!has_next) break;
	v_pk_mul_f32 v[72:73], v[72:73], v[180:181] op_sel_hi:[1,0]
	v_cvt_pk_bf16_f32 v74, v74, v75
	v_cvt_pk_bf16_f32 v75, v76, v77
	v_cvt_pk_bf16_f32 v76, v78, v79
	v_cvt_pk_bf16_f32 v77, v80, v81
	global_store_dwordx4 v[86:87], v[74:77], off
	v_pk_mul_f32 v[70:71], v[70:71], v[180:181] op_sel_hi:[1,0]
	v_pk_mul_f32 v[64:65], v[64:65], v[182:183] op_sel_hi:[1,0]
	v_pk_mul_f32 v[74:75], v[68:69], v[180:181] op_sel_hi:[1,0]
	v_pk_mul_f32 v[68:69], v[66:67], v[180:181] op_sel_hi:[1,0]
	v_cvt_pk_bf16_f32 v66, v70, v71
	v_cvt_pk_bf16_f32 v67, v72, v73
	v_cvt_pk_bf16_f32 v68, v68, v69
	v_cvt_pk_bf16_f32 v69, v74, v75
	global_store_dwordx4 v[86:87], v[66:69], off offset:256
	v_pk_mul_f32 v[62:63], v[62:63], v[182:183] op_sel_hi:[1,0]
	v_rsq_f32_e32 v184, v183
	v_mad_i64_i32 v[66:67], s[22:23], v179, s40, v[146:147]
	v_pk_mul_f32 v[68:69], v[60:61], v[182:183] op_sel_hi:[1,0]
	v_pk_mul_f32 v[60:61], v[58:59], v[182:183] op_sel_hi:[1,0]
	v_lshl_add_u64 v[66:67], v[66:67], 0, v[164:165]
	v_cvt_pk_bf16_f32 v58, v62, v63
	v_cvt_pk_bf16_f32 v59, v64, v65
	v_cvt_pk_bf16_f32 v60, v60, v61
	v_cvt_pk_bf16_f32 v61, v68, v69
	global_store_dwordx4 v[66:67], v[58:61], off
	v_pk_mul_f32 v[52:53], v[52:53], v[182:183] op_sel_hi:[1,0]
	v_pk_mul_f32 v[50:51], v[50:51], v[182:183] op_sel_hi:[1,0]
	v_pk_mul_f32 v[58:59], v[44:45], v[182:183] op_sel_hi:[1,0]
	v_pk_mul_f32 v[44:45], v[42:43], v[182:183] op_sel_hi:[1,0]
	v_cvt_pk_bf16_f32 v42, v50, v51
	v_cvt_pk_bf16_f32 v43, v52, v53
	v_cvt_pk_bf16_f32 v44, v44, v45
	v_cvt_pk_bf16_f32 v45, v58, v59
	global_store_dwordx4 v[66:67], v[42:45], off offset:256
	v_pk_mul_f32 v[48:49], v[48:49], v[184:185] op_sel_hi:[1,0]
	v_pk_mul_f32 v[46:47], v[46:47], v[184:185] op_sel_hi:[1,0]
	v_add_u32_e32 v42, 0x90, v148
	v_mad_i64_i32 v[42:43], s[22:23], v42, s40, v[146:147]
	v_lshl_add_u64 v[50:51], v[42:43], 0, v[164:165]
	v_pk_mul_f32 v[44:45], v[56:57], v[184:185] op_sel_hi:[1,0]
	v_pk_mul_f32 v[42:43], v[54:55], v[184:185] op_sel_hi:[1,0]
	v_pk_mul_f32 v[36:37], v[36:37], v[184:185] op_sel_hi:[1,0]
	v_cvt_pk_bf16_f32 v42, v42, v43
	v_cvt_pk_bf16_f32 v43, v44, v45
	v_cvt_pk_bf16_f32 v44, v46, v47
	v_cvt_pk_bf16_f32 v45, v48, v49
	global_store_dwordx4 v[50:51], v[42:45], off
	v_pk_mul_f32 v[34:35], v[34:35], v[184:185] op_sel_hi:[1,0]
	v_pk_mul_f32 v[32:33], v[32:33], v[186:187] op_sel_hi:[1,0]
	v_pk_mul_f32 v[42:43], v[28:29], v[184:185] op_sel_hi:[1,0]
	v_pk_mul_f32 v[28:29], v[26:27], v[184:185] op_sel_hi:[1,0]
	v_cvt_pk_bf16_f32 v26, v34, v35
	v_cvt_pk_bf16_f32 v27, v36, v37
	v_cvt_pk_bf16_f32 v28, v28, v29
	v_cvt_pk_bf16_f32 v29, v42, v43
	global_store_dwordx4 v[50:51], v[26:29], off offset:256
	v_pk_mul_f32 v[30:31], v[30:31], v[186:187] op_sel_hi:[1,0]
	v_rsq_f32_e32 v150, v185
	v_add_u32_e32 v26, 0xa0, v148
	v_mad_i64_i32 v[26:27], s[22:23], v26, s40, v[146:147]
	v_lshl_add_u64 v[34:35], v[26:27], 0, v[164:165]
	v_pk_mul_f32 v[28:29], v[40:41], v[186:187] op_sel_hi:[1,0]
	v_pk_mul_f32 v[26:27], v[38:39], v[186:187] op_sel_hi:[1,0]
	v_pk_mul_f32 v[20:21], v[20:21], v[186:187] op_sel_hi:[1,0]
	v_cvt_pk_bf16_f32 v26, v26, v27
	v_cvt_pk_bf16_f32 v27, v28, v29
	v_cvt_pk_bf16_f32 v28, v30, v31
	v_cvt_pk_bf16_f32 v29, v32, v33
	global_store_dwordx4 v[34:35], v[26:29], off
	v_pk_mul_f32 v[18:19], v[18:19], v[186:187] op_sel_hi:[1,0]
	v_pk_mul_f32 v[16:17], v[16:17], v[150:151] op_sel_hi:[1,0]
	v_pk_mul_f32 v[26:27], v[12:13], v[186:187] op_sel_hi:[1,0]
	v_pk_mul_f32 v[12:13], v[10:11], v[186:187] op_sel_hi:[1,0]
	v_cvt_pk_bf16_f32 v10, v18, v19
	v_cvt_pk_bf16_f32 v11, v20, v21
	v_cvt_pk_bf16_f32 v12, v12, v13
	v_cvt_pk_bf16_f32 v13, v26, v27
	global_store_dwordx4 v[34:35], v[10:13], off offset:256
	v_pk_mul_f32 v[14:15], v[14:15], v[150:151] op_sel_hi:[1,0]
	v_pk_mul_f32 v[8:9], v[8:9], v[150:151] op_sel_hi:[1,0]
	v_mad_i64_i32 v[10:11], s[22:23], v181, s40, v[146:147]
	v_lshl_add_u64 v[18:19], v[10:11], 0, v[164:165]
	v_pk_mul_f32 v[12:13], v[24:25], v[150:151] op_sel_hi:[1,0]
	v_pk_mul_f32 v[10:11], v[22:23], v[150:151] op_sel_hi:[1,0]
	v_pk_mul_f32 v[6:7], v[6:7], v[150:151] op_sel_hi:[1,0]
	v_cvt_pk_bf16_f32 v10, v10, v11
	v_cvt_pk_bf16_f32 v11, v12, v13
	v_cvt_pk_bf16_f32 v12, v14, v15
	v_cvt_pk_bf16_f32 v13, v16, v17
	global_store_dwordx4 v[18:19], v[10:13], off
	s_nop 1
	v_pk_mul_f32 v[10:11], v[4:5], v[150:151] op_sel_hi:[1,0]
	v_pk_mul_f32 v[4:5], v[2:3], v[150:151] op_sel_hi:[1,0]
	v_cvt_pk_bf16_f32 v2, v6, v7
	v_cvt_pk_bf16_f32 v3, v8, v9
	v_cvt_pk_bf16_f32 v4, v4, v5
	v_cvt_pk_bf16_f32 v5, v10, v11
	global_store_dwordx4 v[18:19], v[2:5], off offset:256
	s_cmp_eq_u64 s[10:11], 0
	s_cbranch_scc1 .Lg3_noalign
	s_barrier
